# gate/up: M0 write, DMA address add and base-pointer SALU at the head of load segments 2 and 4 hoisted into the preceding MFMA shadow
# speedup vs baseline: 1.0057x; 1.0003x over previous
.LBB0_3116:
	v_add_u32_e32 v142, s26, v144
	ds_read_b128 v[146:149], v142
	ds_read_b128 v[150:153], v142 offset:1024
	ds_read_b128 v[154:157], v142 offset:2048
	ds_read_b128 v[158:161], v142 offset:3072
	v_add_u32_e32 v142, s40, v144
	ds_read_b128 v[162:165], v142
	ds_read_b128 v[166:169], v142 offset:1024
	ds_read_b128 v[170:173], v142 offset:2048
	ds_read_b128 v[174:177], v142 offset:3072
	s_add_u32 s18, s34, 0xfff80080
	s_addc_u32 s19, s35, -1
	s_cmp_eq_u32 s74, 28
	s_cselect_b32 s39, s13, s19
	s_cselect_b32 s38, s69, s18
	s_cselect_b32 s19, s11, s73
	s_cselect_b32 s18, s70, s71
	v_lshl_add_u64 v[142:143], s[34:35], 0, v[138:139]
	s_add_i32 m0, s43, 0xc000
	ds_read_b128 v[178:181], v145
	ds_read_b128 v[182:185], v145 offset:1024
	ds_read_b128 v[186:189], v145 offset:2048
	ds_read_b128 v[190:193], v145 offset:3072
	ds_read_b128 v[194:197], v145 offset:4096
	ds_read_b128 v[198:201], v145 offset:5120
	ds_read_b128 v[202:205], v145 offset:6144
	ds_read_b128 v[206:209], v145 offset:7168
	global_load_lds_dwordx4 v[142:143], off
	v_lshl_add_u64 v[142:143], s[34:35], 0, v[140:141]
	s_add_i32 m0, s43, 0xe000
	s_nop 0
	global_load_lds_dwordx4 v[142:143], off
	s_waitcnt vmcnt(8)
	s_waitcnt lgkmcnt(0)
	s_setprio 1
	s_barrier
	v_mfma_f32_16x16x32_bf16 v[128:131], v[146:149], v[178:181], v[128:131]
	v_mfma_f32_16x16x32_bf16 v[128:131], v[150:153], v[182:185], v[128:131]
	v_mfma_f32_16x16x32_bf16 v[112:115], v[146:149], v[186:189], v[112:115]
	v_mfma_f32_16x16x32_bf16 v[112:115], v[150:153], v[190:193], v[112:115]
	v_mfma_f32_16x16x32_bf16 v[96:99], v[146:149], v[194:197], v[96:99]
	v_mfma_f32_16x16x32_bf16 v[96:99], v[150:153], v[198:201], v[96:99]
	v_mfma_f32_16x16x32_bf16 v[80:83], v[146:149], v[202:205], v[80:83]
	v_mfma_f32_16x16x32_bf16 v[80:83], v[150:153], v[206:209], v[80:83]
	v_mfma_f32_16x16x32_bf16 v[72:75], v[154:157], v[202:205], v[72:75]
	v_mfma_f32_16x16x32_bf16 v[72:75], v[158:161], v[206:209], v[72:75]
	v_mfma_f32_16x16x32_bf16 v[88:91], v[154:157], v[194:197], v[88:91]
	v_mfma_f32_16x16x32_bf16 v[88:91], v[158:161], v[198:201], v[88:91]
	v_mfma_f32_16x16x32_bf16 v[104:107], v[154:157], v[186:189], v[104:107]
	v_mfma_f32_16x16x32_bf16 v[104:107], v[158:161], v[190:193], v[104:107]
	v_mfma_f32_16x16x32_bf16 v[120:123], v[154:157], v[178:181], v[120:123]
	v_mfma_f32_16x16x32_bf16 v[120:123], v[158:161], v[182:185], v[120:123]
	s_setprio 0
	s_setprio 1
	v_mfma_f32_16x16x32_bf16 v[124:127], v[162:165], v[178:181], v[124:127]
	v_mfma_f32_16x16x32_bf16 v[124:127], v[166:169], v[182:185], v[124:127]
	v_mfma_f32_16x16x32_bf16 v[108:111], v[162:165], v[186:189], v[108:111]
	v_mfma_f32_16x16x32_bf16 v[108:111], v[166:169], v[190:193], v[108:111]
	v_mfma_f32_16x16x32_bf16 v[92:95], v[162:165], v[194:197], v[92:95]
	v_mfma_f32_16x16x32_bf16 v[92:95], v[166:169], v[198:201], v[92:95]
	v_mfma_f32_16x16x32_bf16 v[76:79], v[162:165], v[202:205], v[76:79]
	v_mfma_f32_16x16x32_bf16 v[76:79], v[166:169], v[206:209], v[76:79]
	s_mov_b32 m0, s27
	v_lshl_add_u64 v[142:143], s[18:19], 0, v[2:3]
	s_add_u32 s76, s18, 0x80000
	s_addc_u32 s77, s19, 0
	v_mfma_f32_16x16x32_bf16 v[68:71], v[170:173], v[202:205], v[68:71]
	v_mfma_f32_16x16x32_bf16 v[68:71], v[174:177], v[206:209], v[68:71]
	v_mfma_f32_16x16x32_bf16 v[84:87], v[170:173], v[194:197], v[84:87]
	v_mfma_f32_16x16x32_bf16 v[84:87], v[174:177], v[198:201], v[84:87]
	v_mfma_f32_16x16x32_bf16 v[100:103], v[170:173], v[186:189], v[100:103]
	v_mfma_f32_16x16x32_bf16 v[100:103], v[174:177], v[190:193], v[100:103]
	v_mfma_f32_16x16x32_bf16 v[116:119], v[170:173], v[178:181], v[116:119]
	v_mfma_f32_16x16x32_bf16 v[116:119], v[174:177], v[182:185], v[116:119]
	s_setprio 0
	s_barrier
	ds_read_b128 v[178:181], v145 offset:16384
	ds_read_b128 v[182:185], v145 offset:17408
	ds_read_b128 v[186:189], v145 offset:18432
	ds_read_b128 v[190:193], v145 offset:19456
	ds_read_b128 v[194:197], v145 offset:20480
	ds_read_b128 v[198:201], v145 offset:21504
	ds_read_b128 v[202:205], v145 offset:22528
	ds_read_b128 v[206:209], v145 offset:23552
	global_load_lds_dwordx4 v[142:143], off
	v_lshl_add_u64 v[210:211], s[18:19], 0, v[132:133]
	s_mov_b32 m0, s37
	global_load_lds_dwordx4 v[210:211], off
	v_lshl_add_u64 v[212:213], s[76:77], 0, v[2:3]
	s_mov_b32 m0, s41
	v_lshl_add_u64 v[214:215], s[38:39], 0, v[134:135]
	global_load_lds_dwordx4 v[212:213], off
	v_lshl_add_u64 v[212:213], s[76:77], 0, v[132:133]
	s_mov_b32 m0, s42
	s_nop 0
	global_load_lds_dwordx4 v[212:213], off
	v_lshl_add_u64 v[212:213], s[38:39], 0, v[136:137]
	s_mov_b32 m0, s43
	s_nop 0
	global_load_lds_dwordx4 v[212:213], off
	s_mov_b32 m0, s44
	s_nop 0
	global_load_lds_dwordx4 v[214:215], off
	s_waitcnt vmcnt(8)
	s_waitcnt lgkmcnt(0)
	s_setprio 1
	s_barrier
	v_mfma_f32_16x16x32_bf16 v[64:67], v[146:149], v[178:181], v[64:67]
	v_mfma_f32_16x16x32_bf16 v[64:67], v[150:153], v[182:185], v[64:67]
	v_mfma_f32_16x16x32_bf16 v[48:51], v[146:149], v[186:189], v[48:51]
	v_mfma_f32_16x16x32_bf16 v[48:51], v[150:153], v[190:193], v[48:51]
	v_mfma_f32_16x16x32_bf16 v[32:35], v[146:149], v[194:197], v[32:35]
	v_mfma_f32_16x16x32_bf16 v[32:35], v[150:153], v[198:201], v[32:35]
	v_mfma_f32_16x16x32_bf16 v[16:19], v[146:149], v[202:205], v[16:19]
	v_mfma_f32_16x16x32_bf16 v[16:19], v[150:153], v[206:209], v[16:19]
	v_mfma_f32_16x16x32_bf16 v[8:11], v[154:157], v[202:205], v[8:11]
	v_mfma_f32_16x16x32_bf16 v[8:11], v[158:161], v[206:209], v[8:11]
	v_mfma_f32_16x16x32_bf16 v[24:27], v[154:157], v[194:197], v[24:27]
	v_mfma_f32_16x16x32_bf16 v[24:27], v[158:161], v[198:201], v[24:27]
	v_mfma_f32_16x16x32_bf16 v[40:43], v[154:157], v[186:189], v[40:43]
	v_mfma_f32_16x16x32_bf16 v[40:43], v[158:161], v[190:193], v[40:43]
	v_mfma_f32_16x16x32_bf16 v[56:59], v[154:157], v[178:181], v[56:59]
	v_mfma_f32_16x16x32_bf16 v[56:59], v[158:161], v[182:185], v[56:59]
	s_setprio 0
	s_setprio 1
	v_mfma_f32_16x16x32_bf16 v[60:63], v[162:165], v[178:181], v[60:63]
	v_mfma_f32_16x16x32_bf16 v[60:63], v[166:169], v[182:185], v[60:63]
	v_mfma_f32_16x16x32_bf16 v[44:47], v[162:165], v[186:189], v[44:47]
	v_mfma_f32_16x16x32_bf16 v[44:47], v[166:169], v[190:193], v[44:47]
	v_mfma_f32_16x16x32_bf16 v[28:31], v[162:165], v[194:197], v[28:31]
	v_mfma_f32_16x16x32_bf16 v[28:31], v[166:169], v[198:201], v[28:31]
	v_mfma_f32_16x16x32_bf16 v[12:15], v[162:165], v[202:205], v[12:15]
	v_mfma_f32_16x16x32_bf16 v[12:15], v[166:169], v[206:209], v[12:15]
	v_mfma_f32_16x16x32_bf16 v[4:7], v[170:173], v[202:205], v[4:7]
	v_mfma_f32_16x16x32_bf16 v[4:7], v[174:177], v[206:209], v[4:7]
	v_mfma_f32_16x16x32_bf16 v[20:23], v[170:173], v[194:197], v[20:23]
	v_mfma_f32_16x16x32_bf16 v[20:23], v[174:177], v[198:201], v[20:23]
	v_mfma_f32_16x16x32_bf16 v[36:39], v[170:173], v[186:189], v[36:39]
	v_mfma_f32_16x16x32_bf16 v[36:39], v[174:177], v[190:193], v[36:39]
	v_mfma_f32_16x16x32_bf16 v[52:55], v[170:173], v[178:181], v[52:55]
	v_mfma_f32_16x16x32_bf16 v[52:55], v[174:177], v[182:185], v[52:55]
	s_setprio 0
	s_barrier
	v_add_u32_e32 v158, s49, v144
	v_add_u32_e32 v174, s56, v144
	ds_read_b128 v[146:149], v158
	ds_read_b128 v[150:153], v158 offset:1024
	ds_read_b128 v[154:157], v158 offset:2048
	ds_read_b128 v[158:161], v158 offset:3072
	ds_read_b128 v[162:165], v174
	ds_read_b128 v[166:169], v174 offset:1024
	ds_read_b128 v[170:173], v174 offset:2048
	ds_read_b128 v[174:177], v174 offset:3072
	s_add_u32 s38, s38, 0x80000
	s_addc_u32 s39, s39, 0
	s_mov_b32 m0, s45
	v_lshl_add_u64 v[216:217], s[38:39], 0, v[136:137]
	ds_read_b128 v[178:181], v145 offset:32768
	ds_read_b128 v[182:185], v145 offset:33792
	ds_read_b128 v[186:189], v145 offset:34816
	ds_read_b128 v[190:193], v145 offset:35840
	ds_read_b128 v[194:197], v145 offset:36864
	ds_read_b128 v[198:201], v145 offset:37888
	ds_read_b128 v[202:205], v145 offset:38912
	ds_read_b128 v[206:209], v145 offset:39936
	global_load_lds_dwordx4 v[216:217], off
	v_lshl_add_u64 v[216:217], s[38:39], 0, v[134:135]
	s_mov_b32 m0, s46
	s_nop 0
	global_load_lds_dwordx4 v[216:217], off
	s_waitcnt vmcnt(8)
	s_waitcnt lgkmcnt(0)
	s_setprio 1
	s_barrier
	v_mfma_f32_16x16x32_bf16 v[128:131], v[146:149], v[178:181], v[128:131]
	v_mfma_f32_16x16x32_bf16 v[128:131], v[150:153], v[182:185], v[128:131]
	v_mfma_f32_16x16x32_bf16 v[112:115], v[146:149], v[186:189], v[112:115]
	v_mfma_f32_16x16x32_bf16 v[112:115], v[150:153], v[190:193], v[112:115]
	v_mfma_f32_16x16x32_bf16 v[96:99], v[146:149], v[194:197], v[96:99]
	v_mfma_f32_16x16x32_bf16 v[96:99], v[150:153], v[198:201], v[96:99]
	v_mfma_f32_16x16x32_bf16 v[80:83], v[146:149], v[202:205], v[80:83]
	v_mfma_f32_16x16x32_bf16 v[80:83], v[150:153], v[206:209], v[80:83]
	v_mfma_f32_16x16x32_bf16 v[72:75], v[154:157], v[202:205], v[72:75]
	v_mfma_f32_16x16x32_bf16 v[72:75], v[158:161], v[206:209], v[72:75]
	v_mfma_f32_16x16x32_bf16 v[88:91], v[154:157], v[194:197], v[88:91]
	v_mfma_f32_16x16x32_bf16 v[88:91], v[158:161], v[198:201], v[88:91]
	v_mfma_f32_16x16x32_bf16 v[104:107], v[154:157], v[186:189], v[104:107]
	v_mfma_f32_16x16x32_bf16 v[104:107], v[158:161], v[190:193], v[104:107]
	v_mfma_f32_16x16x32_bf16 v[120:123], v[154:157], v[178:181], v[120:123]
	v_mfma_f32_16x16x32_bf16 v[120:123], v[158:161], v[182:185], v[120:123]
	s_setprio 0
	s_setprio 1
	v_mfma_f32_16x16x32_bf16 v[124:127], v[162:165], v[178:181], v[124:127]
	v_mfma_f32_16x16x32_bf16 v[124:127], v[166:169], v[182:185], v[124:127]
	v_mfma_f32_16x16x32_bf16 v[108:111], v[162:165], v[186:189], v[108:111]
	v_mfma_f32_16x16x32_bf16 v[108:111], v[166:169], v[190:193], v[108:111]
	v_mfma_f32_16x16x32_bf16 v[92:95], v[162:165], v[194:197], v[92:95]
	v_mfma_f32_16x16x32_bf16 v[92:95], v[166:169], v[198:201], v[92:95]
	v_mfma_f32_16x16x32_bf16 v[76:79], v[162:165], v[202:205], v[76:79]
	v_mfma_f32_16x16x32_bf16 v[76:79], v[166:169], v[206:209], v[76:79]
	s_mov_b32 m0, s50
	v_lshl_add_u64 v[142:143], v[142:143], 0, s[64:65]
	s_add_u32 s18, s18, 0x80080
	s_addc_u32 s19, s19, 0
	v_mfma_f32_16x16x32_bf16 v[68:71], v[170:173], v[202:205], v[68:71]
	v_mfma_f32_16x16x32_bf16 v[68:71], v[174:177], v[206:209], v[68:71]
	v_mfma_f32_16x16x32_bf16 v[84:87], v[170:173], v[194:197], v[84:87]
	v_mfma_f32_16x16x32_bf16 v[84:87], v[174:177], v[198:201], v[84:87]
	v_mfma_f32_16x16x32_bf16 v[100:103], v[170:173], v[186:189], v[100:103]
	v_mfma_f32_16x16x32_bf16 v[100:103], v[174:177], v[190:193], v[100:103]
	v_mfma_f32_16x16x32_bf16 v[116:119], v[170:173], v[178:181], v[116:119]
	v_mfma_f32_16x16x32_bf16 v[116:119], v[174:177], v[182:185], v[116:119]
	s_setprio 0
	s_barrier
	ds_read_b128 v[178:181], v145 offset:49152
	ds_read_b128 v[182:185], v145 offset:50176
	ds_read_b128 v[186:189], v145 offset:51200
	ds_read_b128 v[190:193], v145 offset:52224
	ds_read_b128 v[194:197], v145 offset:53248
	ds_read_b128 v[198:201], v145 offset:54272
	ds_read_b128 v[202:205], v145 offset:55296
	ds_read_b128 v[206:209], v145 offset:56320
	global_load_lds_dwordx4 v[142:143], off
	v_lshl_add_u64 v[142:143], v[210:211], 0, s[64:65]
	s_mov_b32 m0, s51
	global_load_lds_dwordx4 v[142:143], off
	v_lshl_add_u64 v[142:143], s[18:19], 0, v[2:3]
	s_mov_b32 m0, s57
	s_nop 0
	global_load_lds_dwordx4 v[142:143], off
	v_lshl_add_u64 v[142:143], s[18:19], 0, v[132:133]
	s_mov_b32 m0, s58
	s_nop 0
	global_load_lds_dwordx4 v[142:143], off
	v_lshl_add_u64 v[142:143], v[212:213], 0, s[64:65]
	s_mov_b32 m0, s52
	s_nop 0
	global_load_lds_dwordx4 v[142:143], off
	v_lshl_add_u64 v[142:143], v[214:215], 0, s[64:65]
	s_mov_b32 m0, s53
	s_nop 0
	global_load_lds_dwordx4 v[142:143], off
	s_waitcnt vmcnt(8)
	s_waitcnt lgkmcnt(0)
	s_setprio 1
	s_barrier
	v_mfma_f32_16x16x32_bf16 v[64:67], v[146:149], v[178:181], v[64:67]
	v_mfma_f32_16x16x32_bf16 v[64:67], v[150:153], v[182:185], v[64:67]
	v_mfma_f32_16x16x32_bf16 v[48:51], v[146:149], v[186:189], v[48:51]
	v_mfma_f32_16x16x32_bf16 v[48:51], v[150:153], v[190:193], v[48:51]
	v_mfma_f32_16x16x32_bf16 v[32:35], v[146:149], v[194:197], v[32:35]
	v_mfma_f32_16x16x32_bf16 v[32:35], v[150:153], v[198:201], v[32:35]
	v_mfma_f32_16x16x32_bf16 v[16:19], v[146:149], v[202:205], v[16:19]
	v_mfma_f32_16x16x32_bf16 v[16:19], v[150:153], v[206:209], v[16:19]
	v_mfma_f32_16x16x32_bf16 v[8:11], v[154:157], v[202:205], v[8:11]
	v_mfma_f32_16x16x32_bf16 v[8:11], v[158:161], v[206:209], v[8:11]
	v_mfma_f32_16x16x32_bf16 v[24:27], v[154:157], v[194:197], v[24:27]
	v_mfma_f32_16x16x32_bf16 v[24:27], v[158:161], v[198:201], v[24:27]
	v_mfma_f32_16x16x32_bf16 v[40:43], v[154:157], v[186:189], v[40:43]
	v_mfma_f32_16x16x32_bf16 v[40:43], v[158:161], v[190:193], v[40:43]
	v_mfma_f32_16x16x32_bf16 v[56:59], v[154:157], v[178:181], v[56:59]
	v_mfma_f32_16x16x32_bf16 v[56:59], v[158:161], v[182:185], v[56:59]
	s_setprio 0
	s_setprio 1
	v_mfma_f32_16x16x32_bf16 v[60:63], v[162:165], v[178:181], v[60:63]
	v_mfma_f32_16x16x32_bf16 v[60:63], v[166:169], v[182:185], v[60:63]
	v_mfma_f32_16x16x32_bf16 v[44:47], v[162:165], v[186:189], v[44:47]
	v_mfma_f32_16x16x32_bf16 v[44:47], v[166:169], v[190:193], v[44:47]
	v_mfma_f32_16x16x32_bf16 v[28:31], v[162:165], v[194:197], v[28:31]
	v_mfma_f32_16x16x32_bf16 v[28:31], v[166:169], v[198:201], v[28:31]
	v_mfma_f32_16x16x32_bf16 v[12:15], v[162:165], v[202:205], v[12:15]
	v_mfma_f32_16x16x32_bf16 v[12:15], v[166:169], v[206:209], v[12:15]
	s_add_i32 s74, s74, 2
	v_mfma_f32_16x16x32_bf16 v[4:7], v[170:173], v[202:205], v[4:7]
	v_mfma_f32_16x16x32_bf16 v[4:7], v[174:177], v[206:209], v[4:7]
	s_add_u32 s34, s34, 0x100
	s_addc_u32 s35, s35, 0
	v_mfma_f32_16x16x32_bf16 v[20:23], v[170:173], v[194:197], v[20:23]
	v_mfma_f32_16x16x32_bf16 v[20:23], v[174:177], v[198:201], v[20:23]
	s_add_u32 s71, s71, 0x100
	s_addc_u32 s73, s73, 0
	v_mfma_f32_16x16x32_bf16 v[36:39], v[170:173], v[186:189], v[36:39]
	v_mfma_f32_16x16x32_bf16 v[36:39], v[174:177], v[190:193], v[36:39]
	s_cmp_gt_u32 s74, 29
	v_mfma_f32_16x16x32_bf16 v[52:55], v[170:173], v[178:181], v[52:55]
	v_mfma_f32_16x16x32_bf16 v[52:55], v[174:177], v[182:185], v[52:55]
	s_setprio 0
	s_barrier
	s_cbranch_scc0 .LBB0_3116
	s_and_b64 vcc, exec, s[8:9]
	s_cbranch_vccz .LBB0_3119
	s_barrier
